# P9 idle CUs also convert half of the FFN2 gate matrix (P4 keeps jobs < 352)
# speedup vs baseline: 1.0003x; 1.0003x over previous
; #define LAS __attribute__((address_space(3)))
; #define CVT_DECODE_P4(J, it_) do { int r = (it_); J.ok = false; \
;             CVT_DEC(J, args.in[28], D, FF, WGU, 1, args.in[27]) CVT_DEC(J, args.in[29], D, FF, WGU, 2, args.in[27]) CVT_DEC(J, args.in[30], FF, D, WD, 0, nogam) } while (0)
; __device__ __forceinline__ void cvt_load(const CvtJob& J, f32x4 (&cv)[8], int wave, int lane) {
;     ...
;     for (int i = 0; i < 8; ++i) { const int k = k0 + wave + 8 * i;
;         cv[i] = nok ? *(const f32x4*)(J.W + (size_t)k * J.N + n0 + 4 * lane) : (f32x4){0.f, 0.f, 0.f, 0.f};
;         if (J.gam) cv[i] = cv[i] * J.gam[k]; }
; }
; __device__ __forceinline__ void cvt_to_lds(const f32x4 (&cv)[8], LAS unsigned char* lds, int wave, int lane) {
; #pragma unroll
;     for (int i = 0; i < 8; ++i) { const int k = wave + 8 * i; *(LAS f32x4*)(lds + (size_t)k * 1024 + (((4 * lane) ^ (4 * (k >> 3))) * 4)) = cv[i]; }
; __global__ void __launch_bounds__(512, 2) mega_fwd(Args args) {
;     ...
; #pragma unroll 1
;         for (int rep = 0; rep < args.ph_lo + 1 + DUP_CVT4; ++rep)
;         {
;             CvtJob cur, nxt; f32x4 cv[8]; int it = cu;
;             CVT_DECODE_P4(cur, it); if (cur.ok) cvt_load(cur, cv, wave, lane);
;             while (cur.ok) {
;                 cvt_to_lds(cv, lds, wave, lane);
;                 __syncthreads();
;                 it += G; CVT_DECODE_P4(nxt, it); if (nxt.ok) cvt_load(nxt, cv, wave, lane);
.LBB0_649:
	s_cmpk_lt_i32 s16, 0x2c0
	s_mov_b64 s[6:7], -1
	s_waitcnt vmcnt(0)
	v_pk_mul_f32 v[4:5], v[4:5], v[70:71] op_sel_hi:[1,0]
	v_pk_mul_f32 v[2:3], v[2:3], v[70:71] op_sel_hi:[1,0]
	v_pk_mul_f32 v[8:9], v[8:9], v[72:73] op_sel_hi:[1,0]
	v_pk_mul_f32 v[6:7], v[6:7], v[72:73] op_sel_hi:[1,0]
	v_pk_mul_f32 v[12:13], v[12:13], v[74:75] op_sel_hi:[1,0]
	v_pk_mul_f32 v[10:11], v[10:11], v[74:75] op_sel_hi:[1,0]
	v_pk_mul_f32 v[16:17], v[16:17], v[76:77] op_sel_hi:[1,0]
	v_pk_mul_f32 v[14:15], v[14:15], v[76:77] op_sel_hi:[1,0]
	v_pk_mul_f32 v[20:21], v[20:21], v[78:79] op_sel_hi:[1,0]
	v_pk_mul_f32 v[18:19], v[18:19], v[78:79] op_sel_hi:[1,0]
	v_pk_mul_f32 v[24:25], v[24:25], v[80:81] op_sel_hi:[1,0]
	v_pk_mul_f32 v[22:23], v[22:23], v[80:81] op_sel_hi:[1,0]
	v_pk_mul_f32 v[28:29], v[28:29], v[82:83] op_sel_hi:[1,0]
	v_pk_mul_f32 v[26:27], v[26:27], v[82:83] op_sel_hi:[1,0]
	v_pk_mul_f32 v[32:33], v[32:33], v[84:85] op_sel_hi:[1,0]
	v_pk_mul_f32 v[30:31], v[30:31], v[84:85] op_sel_hi:[1,0]
	v_mov_b32_e32 v70, 1.0
	v_mov_b32_e32 v72, 1.0
	v_mov_b32_e32 v74, 1.0
	v_mov_b32_e32 v76, 1.0
	v_mov_b32_e32 v78, 1.0
	v_mov_b32_e32 v80, 1.0
	v_mov_b32_e32 v82, 1.0
	v_mov_b32_e32 v84, 1.0
	ds_write_b128 v60, v[2:5]
	ds_write_b128 v61, v[6:9]
	ds_write_b128 v62, v[10:13]
	ds_write_b128 v63, v[14:17]
	ds_write_b128 v64, v[18:21]
	ds_write_b128 v65, v[22:25]
	ds_write_b128 v66, v[26:29]
	ds_write_b128 v67, v[30:33]
	s_waitcnt lgkmcnt(0)
	s_barrier
	s_cmp_eq_u32 s94, 2
	s_cbranch_scc0 .Lcvt_nm
	s_cmpk_ge_i32 s16, 0x160
	s_cbranch_scc1 .Lcvt_stop
.Lcvt_nm:
	s_cmpk_lt_i32 s16, 0x2c0
	s_cbranch_scc1 .LBB0_651
	s_add_i32 s12, s16, 0xfffffd40
	s_cmpk_lt_u32 s12, 0x2c0
	s_cselect_b64 s[8:9], -1, 0
	s_add_i32 s13, s16, 0xfffffa80
	s_and_b64 s[10:11], s[8:9], exec
	s_cselect_b32 s55, s27, s55
	s_cselect_b32 s54, s26, s54
	s_cselect_b32 s53, s87, s53
	s_cselect_b32 s52, s86, s52
	s_cselect_b32 s45, s23, s45
	s_cselect_b32 s44, s22, s44
	s_cselect_b32 s77, 0x800, s77
	s_cselect_b32 s76, 0x1600, s76
	s_cselect_b32 s75, 2, s75
	s_cselect_b32 s78, s12, s78
	s_cselect_b32 s10, s12, s13
	s_and_b64 vcc, exec, s[8:9]
	s_cbranch_vccz .LBB0_652
	s_branch .LBB0_654

; #define CVT_DECODE_P4(J, it_) do { int r = (it_); J.ok = false; \
;             CVT_DEC(J, args.in[28], D, FF, WGU, 1, args.in[27]) CVT_DEC(J, args.in[29], D, FF, WGU, 2, args.in[27]) CVT_DEC(J, args.in[30], FF, D, WD, 0, nogam) } while (0)
; __global__ void __launch_bounds__(512, 2) mega_fwd(Args args) {
;     ...
; #pragma unroll 1
;         for (int rep = 0; rep < args.ph_lo + 1 + DUP_CVT4; ++rep)
;         {
;             CvtJob cur, nxt; f32x4 cv[8]; int it = cu;
;             CVT_DECODE_P4(cur, it); if (cur.ok) cvt_load(cur, cv, wave, lane);
;             while (cur.ok) {
;                 cvt_to_lds(cv, lds, wave, lane);
;                 __syncthreads();
;                 it += G; CVT_DECODE_P4(nxt, it); if (nxt.ok) cvt_load(nxt, cv, wave, lane);
.Lp9c_go:
	v_writelane_b32 v237, s4, 0
	v_writelane_b32 v237, s5, 1
	v_writelane_b32 v237, s6, 2
	v_writelane_b32 v237, s7, 3
	v_writelane_b32 v237, s8, 4
	v_writelane_b32 v237, s9, 5
	v_writelane_b32 v237, s10, 6
	v_writelane_b32 v237, s11, 7
	v_writelane_b32 v237, s12, 8
	v_writelane_b32 v237, s22, 9
	v_writelane_b32 v237, s23, 10
	v_writelane_b32 v237, s24, 11
	v_writelane_b32 v237, s25, 12
	v_writelane_b32 v237, s26, 13
	v_writelane_b32 v237, s27, 14
	v_writelane_b32 v237, s28, 15
	v_writelane_b32 v237, s29, 16
	v_writelane_b32 v237, s36, 17
	v_writelane_b32 v237, s37, 18
	v_writelane_b32 v237, s44, 19
	v_writelane_b32 v237, s45, 20
	v_writelane_b32 v237, s82, 21
	v_writelane_b32 v237, s84, 22
	v_writelane_b32 v237, s85, 23
	v_writelane_b32 v237, s90, 24
	v_writelane_b32 v237, s80, 25
	s_add_i32 s80, s95, 0x160
	s_movk_i32 s15, 0x60
	s_mov_b32 s94, 1
	v_readlane_b32 s4, v238, 0
	v_readlane_b32 s5, v238, 1
	s_add_u32 s4, s4, 0xfffffee8
	s_addc_u32 s5, s5, -1
	s_load_dwordx2 s[22:23], s[4:5], 0xd8
	s_load_dwordx4 s[24:27], s[4:5], 0xe0
	s_load_dwordx2 s[28:29], s[4:5], 0xf0
	v_readlane_b32 s84, v238, 51
	v_readlane_b32 s85, v238, 52
	v_readlane_b32 s90, v238, 37
	s_waitcnt vmcnt(0) lgkmcnt(0)
	s_branch .Lcvt_entry
